# XCC start stagger removed (0 ticks)
# speedup vs baseline: 1.0038x; 1.0038x over previous
.LBB0_199:
	s_xor_b64 s[0:1], s[0:1], -1
	s_and_b32 s6, s95, 7
	v_writelane_b32 v252, s0, 33
	s_and_b64 vcc, exec, s[0:1]
	s_nop 0
	v_writelane_b32 v252, s1, 34
	s_cbranch_vccnz .LBB0_203
	s_memrealtime s[0:1]
	s_memrealtime s[4:5]
	s_mul_i32 s2, s6, 0
	s_mov_b32 s3, 0
	v_mov_b64_e32 v[2:3], s[2:3]
	s_waitcnt lgkmcnt(0)
	s_sub_u32 s4, s4, s0
	s_subb_u32 s5, s5, s1
	v_cmp_ge_u64_e32 vcc, s[4:5], v[2:3]
	s_cbranch_vccnz .LBB0_203
	v_mov_b64_e32 v[2:3], s[2:3]
